# final-LN phase row loop: four row loads issued together and prefetched one row ahead (were load/wait x4)
# speedup vs baseline: 1.5175x; 1.0006x over previous
.LBB0_612:
	s_cmp_ge_i32 s0, s52
	s_cselect_b64 s[2:3], -1, 0
	s_cmp_lt_i32 s0, s53
	s_cselect_b64 s[4:5], -1, 0
	s_and_b64 s[2:3], s[2:3], s[4:5]
	s_andn2_b64 vcc, exec, s[2:3]
	s_cbranch_vccnz .LBB0_619
	s_waitcnt vmcnt(17)
	v_mov_b32_e32 v32, v182
	v_readlane_b32 s0, v251, 17
	v_ashrrev_i32_e32 v0, 6, v32
	s_nop 0
	v_add_u32_e32 v0, s0, v0
	v_readlane_b32 s0, v250, 31
	s_nop 1
	v_mul_lo_u32 v48, v0, s0
	v_add_u32_e32 v0, s0, v48
	v_min_i32_e32 v72, 0x8000, v0
	v_cmp_lt_i32_e32 vcc, v48, v72
	s_and_saveexec_b64 s[2:3], vcc
	s_cbranch_execz .LBB0_618
	v_lshlrev_b32_e32 v0, 2, v32
	s_mul_i32 s0, s71, 0xc00
	v_and_b32_e32 v33, 0xfc, v0
	s_addk_i32 s0, 0x400
	v_or_b32_e32 v0, s0, v33
	v_ashrrev_i32_e32 v1, 31, v0
	v_lshlrev_b64 v[0:1], 2, v[0:1]
	v_lshl_add_u64 v[20:21], s[24:25], 0, v[0:1]
	v_lshl_add_u64 v[28:29], s[26:27], 0, v[0:1]
	global_load_dwordx4 v[0:3], v[20:21], off
	global_load_dwordx4 v[4:7], v[20:21], off offset:1024
	global_load_dwordx4 v[8:11], v[28:29], off
	global_load_dwordx4 v[12:15], v[28:29], off offset:1024
	global_load_dwordx4 v[16:19], v[20:21], off offset:2048
	s_nop 0
	global_load_dwordx4 v[20:23], v[20:21], off offset:3072
	s_nop 0
	global_load_dwordx4 v[24:27], v[28:29], off offset:2048
	s_nop 0
	global_load_dwordx4 v[28:31], v[28:29], off offset:3072
	v_and_b32_e32 v34, 64, v196
	v_add_u32_e32 v34, 64, v34
	v_xor_b32_e32 v35, 1, v196
	v_cmp_lt_i32_e32 vcc, v35, v34
	v_ashrrev_i32_e32 v49, 31, v48
	v_lshlrev_b32_e32 v112, 2, v33
	v_cndmask_b32_e32 v35, v196, v35, vcc
	v_lshlrev_b32_e32 v73, 2, v35
	v_xor_b32_e32 v35, 2, v196
	v_cmp_lt_i32_e32 vcc, v35, v34
	v_and_b32_e32 v36, 63, v32
	v_lshlrev_b64 v[32:33], 12, v[48:49]
	v_cndmask_b32_e32 v35, v196, v35, vcc
	v_lshlrev_b32_e32 v74, 2, v35
	v_xor_b32_e32 v35, 4, v196
	v_cmp_lt_i32_e32 vcc, v35, v34
	v_readlane_b32 s4, v250, 41
	v_lshl_or_b32 v32, v36, 4, v32
	v_cndmask_b32_e32 v35, v196, v35, vcc
	v_lshlrev_b32_e32 v75, 2, v35
	v_xor_b32_e32 v35, 8, v196
	v_cmp_lt_i32_e32 vcc, v35, v34
	v_readlane_b32 s5, v250, 42
	s_lshl_b32 s0, s71, 2
	v_cndmask_b32_e32 v35, v196, v35, vcc
	v_lshlrev_b32_e32 v76, 2, v35
	v_xor_b32_e32 v35, 16, v196
	v_cmp_lt_i32_e32 vcc, v35, v34
	v_mov_b32_e32 v79, -1
	v_lshl_add_u64 v[50:51], s[50:51], 0, v[112:113]
	v_cndmask_b32_e32 v35, v196, v35, vcc
	v_lshlrev_b32_e32 v77, 2, v35
	v_xor_b32_e32 v35, 32, v196
	v_cmp_lt_i32_e32 vcc, v35, v34
	v_lshl_add_u64 v[54:55], s[4:5], 0, v[32:33]
	s_mov_b64 s[8:9], 0
	v_cndmask_b32_e32 v34, v196, v35, vcc
	v_lshlrev_b32_e32 v78, 2, v34
	v_lshlrev_b64 v[34:35], 11, v[48:49]
	v_lshl_or_b32 v34, v36, 3, v34
	v_lshl_add_u64 v[52:53], s[40:41], 0, v[34:35]
	global_load_dwordx4 v[136:139], v[54:55], off offset:-2048
	global_load_dwordx4 v[140:143], v[54:55], off offset:-1024
	global_load_dwordx4 v[144:147], v[54:55], off
	global_load_dwordx4 v[148:151], v[54:55], off offset:1024
	s_waitcnt vmcnt(0)
	s_branch .LBB0_616

.LBB0_661:
	s_cmp_ge_i32 s0, s52
	s_cselect_b64 s[2:3], -1, 0
	s_cmp_lt_i32 s0, s53
	s_cselect_b64 s[4:5], -1, 0
	s_and_b64 s[2:3], s[2:3], s[4:5]
	s_andn2_b64 vcc, exec, s[2:3]
	s_cbranch_vccnz .LBB0_670
	s_waitcnt vmcnt(17)
	v_mov_b32_e32 v32, v182
	v_readlane_b32 s0, v251, 17
	v_ashrrev_i32_e32 v0, 6, v32
	s_cmp_eq_u32 s71, 0
	v_add_u32_e32 v0, s0, v0
	v_readlane_b32 s0, v250, 31
	s_cselect_b64 s[2:3], -1, 0
	s_nop 0
	v_mul_lo_u32 v64, v0, s0
	v_add_u32_e32 v0, s0, v64
	v_min_i32_e32 v88, 0x8000, v0
	v_cmp_lt_i32_e32 vcc, v64, v88
	s_and_saveexec_b64 s[8:9], vcc
	s_cbranch_execz .LBB0_669
	v_lshlrev_b32_e32 v0, 2, v32
	s_mul_i32 s0, s71, 0xc00
	v_and_b32_e32 v33, 0xfc, v0
	s_addk_i32 s0, 0x800
	v_or_b32_e32 v0, s0, v33
	v_ashrrev_i32_e32 v1, 31, v0
	v_lshlrev_b64 v[0:1], 2, v[0:1]
	v_lshl_add_u64 v[20:21], s[24:25], 0, v[0:1]
	v_lshl_add_u64 v[28:29], s[26:27], 0, v[0:1]
	global_load_dwordx4 v[0:3], v[20:21], off
	global_load_dwordx4 v[4:7], v[20:21], off offset:1024
	global_load_dwordx4 v[8:11], v[28:29], off
	global_load_dwordx4 v[12:15], v[28:29], off offset:1024
	global_load_dwordx4 v[16:19], v[20:21], off offset:2048
	s_nop 0
	global_load_dwordx4 v[20:23], v[20:21], off offset:3072
	s_nop 0
	global_load_dwordx4 v[24:27], v[28:29], off offset:2048
	s_nop 0
	global_load_dwordx4 v[28:31], v[28:29], off offset:3072
	v_and_b32_e32 v34, 64, v196
	v_add_u32_e32 v34, 64, v34
	v_xor_b32_e32 v35, 1, v196
	v_cmp_lt_i32_e32 vcc, v35, v34
	v_ashrrev_i32_e32 v65, 31, v64
	v_lshlrev_b32_e32 v112, 2, v33
	v_cndmask_b32_e32 v35, v196, v35, vcc
	v_lshlrev_b32_e32 v89, 2, v35
	v_xor_b32_e32 v35, 2, v196
	v_cmp_lt_i32_e32 vcc, v35, v34
	v_and_b32_e32 v36, 63, v32
	v_lshlrev_b64 v[32:33], 12, v[64:65]
	v_cndmask_b32_e32 v35, v196, v35, vcc
	v_lshlrev_b32_e32 v90, 2, v35
	v_xor_b32_e32 v35, 4, v196
	v_cmp_lt_i32_e32 vcc, v35, v34
	v_readlane_b32 s4, v250, 41
	v_lshl_or_b32 v32, v36, 4, v32
	v_cndmask_b32_e32 v35, v196, v35, vcc
	v_lshlrev_b32_e32 v91, 2, v35
	v_xor_b32_e32 v35, 8, v196
	v_cmp_lt_i32_e32 vcc, v35, v34
	v_readlane_b32 s5, v250, 42
	v_mov_b32_e32 v95, -1
	v_cndmask_b32_e32 v35, v196, v35, vcc
	v_lshlrev_b32_e32 v92, 2, v35
	v_xor_b32_e32 v35, 16, v196
	v_cmp_lt_i32_e32 vcc, v35, v34
	v_lshl_add_u64 v[66:67], s[50:51], 0, v[112:113]
	v_lshl_add_u64 v[70:71], s[4:5], 0, v[32:33]
	v_cndmask_b32_e32 v35, v196, v35, vcc
	v_lshlrev_b32_e32 v93, 2, v35
	v_xor_b32_e32 v35, 32, v196
	v_cmp_lt_i32_e32 vcc, v35, v34
	s_mov_b64 s[10:11], 0
	s_nop 0
	v_cndmask_b32_e32 v34, v196, v35, vcc
	v_lshlrev_b32_e32 v94, 2, v34
	v_lshlrev_b64 v[34:35], 11, v[64:65]
	v_lshl_or_b32 v34, v36, 3, v34
	v_lshl_add_u64 v[68:69], s[40:41], 0, v[34:35]
	global_load_dwordx4 v[136:139], v[70:71], off offset:-2048
	global_load_dwordx4 v[140:143], v[70:71], off offset:-1024
	global_load_dwordx4 v[144:147], v[70:71], off
	global_load_dwordx4 v[148:151], v[70:71], off offset:1024
	s_waitcnt vmcnt(0)
	s_branch .LBB0_666
.LBB0_664:
	s_or_b64 exec, exec, s[12:13]
	s_waitcnt vmcnt(5)
	v_mov_b32_e32 v48, v136
	v_mov_b32_e32 v49, v137
	v_mov_b32_e32 v50, v138
	v_mov_b32_e32 v51, v139
	v_mov_b32_e32 v52, v140
	v_mov_b32_e32 v53, v141
	v_mov_b32_e32 v54, v142
	v_mov_b32_e32 v55, v143
	v_mov_b32_e32 v56, v144
	v_mov_b32_e32 v57, v145
	v_mov_b32_e32 v58, v146
	v_mov_b32_e32 v59, v147
	v_mov_b32_e32 v60, v148
	v_mov_b32_e32 v61, v149
	v_mov_b32_e32 v62, v150
	v_mov_b32_e32 v63, v151
	v_add_u32_e32 v155, 1, v64
	v_mov_b32_e32 v154, 0x1000
	v_cmp_lt_i32_e32 vcc, v155, v88
	s_nop 1
	v_cndmask_b32_e32 v154, 0, v154, vcc
	v_add_co_u32_e32 v152, vcc, v70, v154
	s_nop 1
	v_addc_co_u32_e32 v153, vcc, 0, v71, vcc
	global_load_dwordx4 v[136:139], v[152:153], off offset:-2048
	global_load_dwordx4 v[140:143], v[152:153], off offset:-1024
	global_load_dwordx4 v[144:147], v[152:153], off
	global_load_dwordx4 v[148:151], v[152:153], off offset:1024
	v_add_f32_e32 v65, 0, v48
	v_add_f32_e32 v65, v65, v49
	v_add_f32_e32 v65, v65, v50
	v_add_f32_e32 v65, v65, v51
	v_add_f32_e32 v65, v65, v52
	v_add_f32_e32 v65, v65, v53
	v_add_f32_e32 v65, v65, v54
	v_add_f32_e32 v65, v65, v55
	v_add_f32_e32 v65, v65, v56
	v_add_f32_e32 v65, v65, v57
	v_add_f32_e32 v65, v65, v58
	v_add_f32_e32 v65, v65, v59
	v_add_f32_e32 v65, v65, v60
	v_add_f32_e32 v65, v65, v61
	v_add_f32_e32 v65, v65, v62
	v_add_f32_e32 v65, v65, v63
	ds_bpermute_b32 v96, v89, v65
	s_waitcnt lgkmcnt(0)
	v_add_f32_e32 v65, v65, v96
	ds_bpermute_b32 v96, v90, v65
	s_waitcnt lgkmcnt(0)
	v_add_f32_e32 v65, v65, v96
	ds_bpermute_b32 v96, v91, v65
	s_waitcnt lgkmcnt(0)
	v_add_f32_e32 v65, v65, v96
	ds_bpermute_b32 v96, v92, v65
	s_waitcnt lgkmcnt(0)
	v_add_f32_e32 v65, v65, v96
	ds_bpermute_b32 v96, v93, v65
	s_waitcnt lgkmcnt(0)
	v_add_f32_e32 v65, v65, v96
	ds_bpermute_b32 v96, v94, v65
	s_waitcnt lgkmcnt(0)
	v_add_f32_e32 v65, v65, v96
	v_mul_f32_e32 v96, 0x3a800000, v65
	v_mov_b32_e32 v252, v96
	v_pk_add_f32 v[48:49], v[48:49], v[96:97] op_sel_hi:[1,0] neg_lo:[0,1] neg_hi:[0,1]
	v_pk_add_f32 v[50:51], v[50:51], v[96:97] op_sel_hi:[1,0] neg_lo:[0,1] neg_hi:[0,1]
	v_pk_mul_f32 v[98:99], v[48:49], v[48:49]
	v_pk_mul_f32 v[100:101], v[50:51], v[50:51]
	v_add_f32_e32 v65, v98, v99
	v_pk_add_f32 v[52:53], v[52:53], v[96:97] op_sel_hi:[1,0] neg_lo:[0,1] neg_hi:[0,1]
	v_add_f32_e32 v65, v100, v65
	v_pk_mul_f32 v[102:103], v[52:53], v[52:53]
	v_add_f32_e32 v65, v101, v65
	v_pk_add_f32 v[54:55], v[54:55], v[96:97] op_sel_hi:[1,0] neg_lo:[0,1] neg_hi:[0,1]
	v_add_f32_e32 v65, v102, v65
	v_pk_mul_f32 v[104:105], v[54:55], v[54:55]
	v_add_f32_e32 v65, v103, v65
	v_pk_add_f32 v[106:107], v[56:57], v[96:97] op_sel_hi:[1,0] neg_lo:[0,1] neg_hi:[0,1]
	v_add_f32_e32 v65, v104, v65
	v_pk_mul_f32 v[56:57], v[106:107], v[106:107]
	v_add_f32_e32 v65, v105, v65
	v_pk_add_f32 v[108:109], v[58:59], v[96:97] op_sel_hi:[1,0] neg_lo:[0,1] neg_hi:[0,1]
	v_add_f32_e32 v56, v56, v65
	v_pk_mul_f32 v[58:59], v[108:109], v[108:109]
	v_add_f32_e32 v56, v57, v56
	v_pk_add_f32 v[110:111], v[60:61], v[96:97] op_sel_hi:[1,0] neg_lo:[0,1] neg_hi:[0,1]
	v_add_f32_e32 v56, v58, v56
	v_pk_mul_f32 v[60:61], v[110:111], v[110:111]
	v_add_f32_e32 v56, v59, v56
	v_pk_add_f32 v[96:97], v[62:63], v[96:97] op_sel_hi:[1,0] neg_lo:[0,1] neg_hi:[0,1]
	v_add_f32_e32 v56, v60, v56
	v_pk_mul_f32 v[62:63], v[96:97], v[96:97]
	v_add_f32_e32 v56, v61, v56
	v_add_f32_e32 v56, v62, v56
	v_add_f32_e32 v56, v63, v56
	ds_bpermute_b32 v57, v89, v56
	s_waitcnt lgkmcnt(0)
	v_add_f32_e32 v56, v56, v57
	ds_bpermute_b32 v57, v90, v56
	s_waitcnt lgkmcnt(0)
	v_add_f32_e32 v56, v56, v57
	ds_bpermute_b32 v57, v91, v56
	s_waitcnt lgkmcnt(0)
	v_add_f32_e32 v56, v56, v57
	ds_bpermute_b32 v57, v92, v56
	s_waitcnt lgkmcnt(0)
	v_add_f32_e32 v56, v56, v57
	ds_bpermute_b32 v57, v93, v56
	s_waitcnt lgkmcnt(0)
	v_add_f32_e32 v56, v56, v57
	ds_bpermute_b32 v57, v94, v56
	s_waitcnt lgkmcnt(0)
	v_add_f32_e32 v56, v56, v57
	v_fmamk_f32 v56, v56, 0x3a800000, v184
	v_cmp_gt_f32_e32 vcc, s49, v56
	v_mul_f32_e32 v57, 0x4b800000, v56
	s_nop 0
	v_cndmask_b32_e32 v56, v56, v57, vcc
	v_rsq_f32_e32 v56, v56
	s_nop 0
	v_mul_f32_e32 v57, 0x45800000, v56
	v_cndmask_b32_e32 v98, v56, v57, vcc
	v_mov_b32_e32 v253, v98
	v_lshlrev_b32_e32 v254, 3, v64
	v_add_u32_e32 v254, 0x1e200000, v254
	s_mov_b64 exec, 1
	global_store_dwordx2 v254, v[252:253], s[30:31]
	s_mov_b64 exec, -1
	v_pk_mul_f32 v[48:49], v[48:49], v[98:99] op_sel_hi:[1,0]
	s_andn2_b64 vcc, exec, s[2:3]
	v_pk_fma_f32 v[60:61], v[0:1], v[48:49], v[8:9]
	v_pk_mul_f32 v[48:49], v[50:51], v[98:99] op_sel_hi:[1,0]
	v_pk_mul_f32 v[50:51], v[96:97], v[98:99] op_sel_hi:[1,0]
	v_pk_fma_f32 v[62:63], v[2:3], v[48:49], v[10:11]
	v_pk_mul_f32 v[48:49], v[52:53], v[98:99] op_sel_hi:[1,0]
	v_pk_fma_f32 v[50:51], v[22:23], v[50:51], v[30:31]
	v_pk_fma_f32 v[56:57], v[4:5], v[48:49], v[12:13]
	v_pk_mul_f32 v[48:49], v[54:55], v[98:99] op_sel_hi:[1,0]
	s_nop 0
	v_pk_fma_f32 v[58:59], v[6:7], v[48:49], v[14:15]
	v_pk_mul_f32 v[48:49], v[106:107], v[98:99] op_sel_hi:[1,0]
	s_nop 0
	v_pk_fma_f32 v[52:53], v[16:17], v[48:49], v[24:25]
	v_pk_mul_f32 v[48:49], v[108:109], v[98:99] op_sel_hi:[1,0]
	s_nop 0
	v_pk_fma_f32 v[54:55], v[18:19], v[48:49], v[26:27]
	v_pk_mul_f32 v[48:49], v[110:111], v[98:99] op_sel_hi:[1,0]
	s_nop 0
	v_pk_fma_f32 v[48:49], v[20:21], v[48:49], v[28:29]
	v_mov_b32_e32 v255, s71
	v_cmp_eq_u32_e64 s[100:101], 1, v255
	s_nop 1
	s_mov_b64 exec, s[100:101]
	global_store_dwordx4 v[70:71], v[60:63], off offset:-2048
	global_store_dwordx4 v[70:71], v[56:59], off offset:-1024
	global_store_dwordx4 v[70:71], v[52:55], off
	global_store_dwordx4 v[70:71], v[48:51], off offset:1024
	s_mov_b64 exec, -1
	s_cbranch_vccz .LBB0_668

.LBB0_666:
	v_ashrrev_i32_e32 v48, 31, v64
	v_lshrrev_b32_e32 v48, 19, v48
	v_add_u32_e32 v48, v64, v48
	v_ashrrev_i32_e32 v48, 13, v48
	v_cmp_ne_u32_e32 vcc, v48, v95
	s_and_b64 s[4:5], s[2:3], vcc
	s_and_saveexec_b64 s[12:13], s[4:5]
	s_cbranch_execz .LBB0_664
	v_add_u32_e32 v32, 4, v48
	v_mul_hi_i32_i24_e32 v33, 0x9000, v32
	v_mul_i32_i24_e32 v32, 0x9000, v32
	v_lshl_add_u64 v[32:33], v[66:67], 0, v[32:33]
	v_add_co_u32_e32 v34, vcc, 0x1000, v32
	v_mov_b32_e32 v95, v48
	s_nop 0
	v_addc_co_u32_e32 v35, vcc, 0, v33, vcc
	global_load_dwordx4 v[50:53], v[34:35], off
	global_load_dwordx4 v[54:57], v[34:35], off offset:1024
	global_load_dwordx4 v[58:61], v[34:35], off offset:2048
	global_load_dwordx4 v[96:99], v[34:35], off offset:3072
	global_load_dwordx4 v[44:47], v[32:33], off
	global_load_dwordx4 v[40:43], v[32:33], off offset:1024
	global_load_dwordx4 v[36:39], v[32:33], off offset:2048
	s_nop 0
	global_load_dwordx4 v[32:35], v[32:33], off offset:3072
	s_waitcnt vmcnt(7)
	v_pk_add_f32 v[82:83], v[50:51], 1.0 op_sel_hi:[1,0]
	v_pk_add_f32 v[80:81], v[52:53], 1.0 op_sel_hi:[1,0]
	s_waitcnt vmcnt(6)
	v_pk_add_f32 v[78:79], v[54:55], 1.0 op_sel_hi:[1,0]
	v_pk_add_f32 v[76:77], v[56:57], 1.0 op_sel_hi:[1,0]
	s_waitcnt vmcnt(5)
	v_pk_add_f32 v[74:75], v[58:59], 1.0 op_sel_hi:[1,0]
	v_pk_add_f32 v[72:73], v[60:61], 1.0 op_sel_hi:[1,0]
	s_waitcnt vmcnt(0)
	v_pk_add_f32 v[86:87], v[96:97], 1.0 op_sel_hi:[1,0]
	v_pk_add_f32 v[84:85], v[98:99], 1.0 op_sel_hi:[1,0]
	s_branch .LBB0_664

.LBB0_669:
	s_waitcnt vmcnt(0)
	s_or_b64 exec, exec, s[8:9]
	v_readlane_b32 s4, v250, 21
	v_readlane_b32 s5, v250, 22
	s_and_b64 s[2:3], s[4:5], s[2:3]
	s_andn2_b64 vcc, exec, s[2:3]
	v_readlane_b32 s0, v251, 0
	s_cbranch_vccz .LBB0_678
